# P0 rebalance: meta-item workgroups keep 3 of 8 RMSNorm row-pair iterations and no weight transposes; the other 176 workgroups take them over
# speedup vs baseline: 1.0127x; 1.0127x over previous
.LBB0_39:
	s_or_b64 exec, exec, s[0:1]
	s_lshl_b32 s0, s84, 3
	v_and_b32_e32 v1, 63, v1
	s_add_i32 s4, s0, s54
	s_lshl_b32 s25, s33, 3
	s_mov_b32 s60, 0
	s_mov_b32 s61, s4
	s_mov_b32 s62, 0x8000
	s_and_b32 s63, s4, 0xff
	s_lshr_b32 s64, s4, 8
	s_mov_b64 s[68:69], s[14:15]
	s_mov_b64 s[70:71], s[16:17]
	s_mov_b64 s[72:73], s[8:9]
	v_lshlrev_b32_e32 v34, 4, v1
	v_lshlrev_b32_e32 v36, 3, v1
	s_cmp_lg_u32 s33, 0x100
	s_cbranch_scc1 .Lmy_p0_a0
	s_cmp_lt_u32 s63, 0x50
	s_cbranch_scc1 .LBB0_42
.Lmy_p0_a0:
	s_cmpk_gt_i32 s4, 0xdff
	s_cbranch_scc1 .LBB0_42
	s_lshl_b32 s0, s54, 14
	s_add_i32 s2, s0, 0
	v_and_b32_e32 v4, 0x70, v34
	v_mov_b32_e32 v5, 0
	v_lshrrev_b32_e32 v1, 3, v1
	v_lshl_add_u64 v[2:3], s[10:11], 0, v[4:5]
	v_add_u32_e32 v10, s2, v4
	v_and_b32_e32 v4, 56, v36
	v_mul_u32_u24_e32 v11, 0x84, v1
	v_mul_u32_u24_e32 v9, 0x84, v4
	v_lshlrev_b32_e32 v4, 1, v4
	v_lshl_add_u64 v[4:5], s[16:17], 0, v[4:5]
	s_mov_b64 s[0:1], 0xc00000
	v_lshlrev_b32_e32 v12, 2, v1
	v_add_u32_e32 v10, v10, v11
	v_or_b32_e32 v6, 8, v1
	v_or_b32_e32 v7, 16, v1
	v_or_b32_e32 v8, 24, v1
	v_lshl_add_u64 v[4:5], v[4:5], 0, s[0:1]
	v_add3_u32 v9, s2, v9, v12
	s_mov_b32 s2, 0xb000
	v_add_u32_e32 v11, 0x420, v10
	v_add_u32_e32 v12, 0x428, v10
	v_add_u32_e32 v13, 0x840, v10
	v_add_u32_e32 v14, 0x848, v10
	v_add_u32_e32 v15, 0xc60, v10
	v_add_u32_e32 v16, 0xc68, v10
	v_add_u32_e32 v17, 0x1080, v10
	v_add_u32_e32 v18, 0x1088, v10
	v_add_u32_e32 v19, 0x14a0, v10
	v_add_u32_e32 v20, 0x14a8, v10
	v_add_u32_e32 v21, 0x18c0, v10
	v_add_u32_e32 v22, 0x18c8, v10
	v_add_u32_e32 v23, 0x1ce0, v10
	v_add_u32_e32 v24, 0x1ce8, v10
	s_movk_i32 s3, 0x7fff
	s_mov_b32 s5, 0xffff0000
	s_mov_b32 s6, s4

.LBB0_42:
	s_movk_i32 s28, 0x7fff
	s_cmp_lg_u32 s33, 0x100
	s_cbranch_scc1 .Lmy_p0_borig
	s_lshl_b32 s25, s33, 3
	s_cmp_lg_u32 s60, 0
	s_cbranch_scc1 .Lmy_p0_bdisp
	s_mov_b32 s60, 1
	s_cmp_lt_u32 s63, 0x50
	s_cbranch_scc1 .Lmy_p0_bdisp
	s_sub_u32 s65, s63, 0x50
	s_movk_i32 s66, 0x50
	s_cmp_lt_u32 s64, 6
	s_cselect_b32 s66, 0xa0, s66
	s_cmp_ge_u32 s65, s66
	s_cbranch_scc1 .Lmy_p0_bdisp
	s_lshl_b32 s6, s64, 8
	s_cmp_ge_u32 s65, 0x50
	s_cbranch_scc0 .Lmy_p0_a1
	s_add_u32 s6, s6, 0x7b0
.Lmy_p0_a1:
	s_add_u32 s6, s6, s65
	s_movk_i32 s25, 0x4000
	s_branch .LBB0_41
.Lmy_p0_borig:
	s_cmpk_gt_i32 s4, 0x7fff
	s_cbranch_scc1 .LBB0_49
	s_branch .Lmy_p0_b43
.Lmy_p0_bdisp:
	s_cmp_lg_u32 s33, 0x100
	s_cbranch_scc1 .LBB0_49
	s_cmp_lg_u32 s60, 1
	s_cbranch_scc1 .Lmy_p0_bx
	s_mov_b32 s60, 2
	s_mov_b32 s4, s61
	s_mov_b32 s62, 0x8000
	s_cmp_lt_u32 s63, 0x50
	s_cbranch_scc0 .Lmy_p0_b43
	s_add_u32 s62, s61, 0x3000
	s_branch .Lmy_p0_b43
.Lmy_p0_bx:
	s_cmp_lt_u32 s63, 0x50
	s_cbranch_scc1 .LBB0_49
	s_cmp_gt_u32 s60, 4
	s_cbranch_scc1 .LBB0_49
	s_sub_u32 s65, s60, 2
	s_mul_i32 s65, s65, 0xb0
	s_add_u32 s65, s65, s63
	s_sub_u32 s65, s65, 0x50
	s_add_u32 s60, s60, 1
	s_cmp_ge_u32 s65, 0x190
	s_cbranch_scc1 .LBB0_49
	s_mul_i32 s66, s65, 0xcd
	s_lshr_b32 s66, s66, 14
	s_mul_i32 s67, s66, 0x50
	s_sub_u32 s65, s65, s67
	s_add_u32 s66, s66, 3
	s_lshl_b32 s66, s66, 12
	s_lshl_b32 s4, s64, 8
	s_add_u32 s4, s4, s65
	s_add_u32 s4, s4, s66
	s_add_u32 s62, s4, 1
	s_mov_b64 s[14:15], s[68:69]
	s_mov_b64 s[16:17], s[70:71]
	s_mov_b64 s[8:9], s[72:73]
.Lmy_p0_b43:
	v_mov_b32_e32 v35, 0
	v_mov_b32_e32 v37, v35
	v_lshl_add_u64 v[2:3], s[16:17], 0, v[36:37]
	s_mov_b64 s[0:1], 0x3a00000
	v_lshl_add_u64 v[40:41], v[2:3], 0, s[0:1]
	s_lshl_b32 s0, s33, 4
	s_ashr_i32 s5, s4, 31
	s_ashr_i32 s1, s0, 31
	v_lshl_add_u64 v[38:39], s[8:9], 0, v[34:35]
	s_lshl_b64 s[6:7], s[4:5], 10
	s_lshl_b64 s[8:9], s[0:1], 10
	s_lshl_b64 s[2:3], s[4:5], 12
	s_add_u32 s10, s14, s2
	s_addc_u32 s11, s15, s3
	s_lshl_b64 s[18:19], s[0:1], 12
	s_lshl_b64 s[2:3], s[4:5], 11
	s_add_u32 s20, s16, s2
	s_addc_u32 s21, s17, s3
	s_add_i32 s2, s4, s25
	s_ashr_i32 s3, s2, 31
	s_lshl_b64 s[22:23], s[0:1], 11
	s_lshl_b64 s[26:27], s[2:3], 11
	s_add_u32 s16, s16, s26
	v_mbcnt_lo_u32_b32 v1, -1, 0
	s_addc_u32 s17, s17, s27
	s_lshl_b64 s[2:3], s[2:3], 12
	v_mbcnt_hi_u32_b32 v1, -1, v1
	s_add_u32 s14, s14, s2
	v_and_b32_e32 v2, 64, v1
	s_addc_u32 s15, s15, s3
	v_mov_b32_e32 v42, 0x358637bd
	s_mov_b32 s24, 0x3a800000
	s_mov_b32 s1, 0x800000
	s_mov_b32 s5, 0xffff0000
	s_mov_b32 s29, 0x3a00000
	v_add_u32_e32 v43, 64, v2
	v_xor_b32_e32 v46, 1, v1
	v_xor_b32_e32 v47, 2, v1
	v_xor_b32_e32 v48, 4, v1
	v_xor_b32_e32 v49, 8, v1
	v_xor_b32_e32 v50, 16, v1
	v_xor_b32_e32 v51, 32, v1
	v_mov_b32_e32 v52, 1
	s_branch .LBB0_45
.LBB0_44:
	s_add_i32 s4, s4, s0
	s_add_u32 s6, s6, s8
	s_addc_u32 s7, s7, s9
	s_add_u32 s10, s10, s18
	s_addc_u32 s11, s11, s19
	s_add_u32 s20, s20, s22
	s_addc_u32 s21, s21, s23
	s_add_u32 s16, s16, s22
	v_bfe_u32 v3, v4, 16, 1
	s_addc_u32 s17, s17, s23
	v_add3_u32 v3, v4, v3, s28
	v_bfe_u32 v4, v5, 16, 1
	s_add_u32 s14, s14, s18
	v_lshrrev_b32_e32 v3, 16, v3
	v_add3_u32 v4, v5, v4, s28
	s_addc_u32 s15, s15, s19
	v_lshl_add_u64 v[6:7], s[2:3], 1, v[40:41]
	v_and_or_b32 v3, v4, s5, v3
	s_cmp_lt_i32 s4, s62
	global_store_dwordx2 v[6:7], v[2:3], off offset:1536
	s_cbranch_scc0 .Lmy_p0_bdisp
